# v55 + norm1 row reduction via DPP adds and permlane16/32 swaps instead of six ds_bpermute LDS round trips
# baseline (speedup 1.0000x reference)
; __device__ __forceinline__ float wave_sum(float v) {
; #pragma unroll
;     for (int o = 1; o < 64; o <<= 1) v += __shfl_xor(v, o);
;     return v;
; }
.Lp1_join:
	s_waitcnt vmcnt(12)
	v_mov_b32_e32 v14, v104
	v_mov_b32_e32 v15, v105
	v_mov_b32_e32 v16, v106
	v_mov_b32_e32 v17, v107
	v_mov_b32_e32 v18, v108
	v_mov_b32_e32 v19, v109
	v_mov_b32_e32 v20, v110
	v_mov_b32_e32 v21, v111
	v_mov_b32_e32 v22, v112
	v_mov_b32_e32 v23, v113
	v_mov_b32_e32 v24, v114
	v_mov_b32_e32 v25, v115
	v_mov_b32_e32 v26, v116
	v_mov_b32_e32 v27, v117
	v_mov_b32_e32 v28, v118
	v_mov_b32_e32 v29, v119
	s_mov_b32 s37, s23
	s_add_i32 s23, s23, s32
	s_add_i32 s36, s23, s32
	s_cmp_ge_i32 s36, s0
	s_cselect_b32 s36, s37, s36
	s_cmp_ge_i32 s23, s0
	s_cselect_b32 s40, 1, 0
	s_mov_b32 s34, s36
	s_cmpk_gt_i32 s34, 0x7fff
	s_cselect_b32 s20, s6, s4
	s_cselect_b32 s21, s7, s5
	s_cselect_b32 s8, 0x8000, 0
	s_sub_i32 s8, s34, s8
	s_lshl_b64 s[38:39], s[8:9], 12
	s_add_u32 s20, s20, s38
	s_addc_u32 s21, s21, s39
	v_lshl_add_u64 v[120:121], s[20:21], 0, v[4:5]
	global_load_dwordx4 v[104:107], v[120:121], off nt
	global_load_dwordx4 v[108:111], v[120:121], off offset:1024 nt
	global_load_dwordx4 v[112:115], v[120:121], off offset:3072 nt
	global_load_dwordx4 v[116:119], v[120:121], off offset:2048 nt
	s_lshl_b64 s[16:17], s[16:17], 11
	v_pk_mul_f32 v[58:59], v[16:17], v[16:17]
	v_pk_mul_f32 v[60:61], v[14:15], v[14:15]
	v_pk_mul_f32 v[62:63], v[20:21], v[20:21]
	v_pk_mul_f32 v[64:65], v[18:19], v[18:19]
	v_pk_mov_b32 v[70:71], v[60:61], v[58:59] op_sel:[1,0]
	v_mov_b32_e32 v61, v59
	v_pk_mov_b32 v[58:59], v[64:65], v[62:63] op_sel:[1,0]
	v_mov_b32_e32 v65, v63
	v_mul_f32_e32 v69, v23, v23
	v_mul_f32_e32 v66, v27, v27
	v_mul_f32_e32 v68, v29, v29
	v_pk_add_f32 v[60:61], v[70:71], v[60:61]
	v_pk_add_f32 v[58:59], v[58:59], v[64:65]
	v_mul_f32_e32 v13, v22, v22
	v_mul_f32_e32 v72, v24, v24
	v_mul_f32_e32 v73, v25, v25
	v_pk_fma_f32 v[62:63], v[26:27], v[26:27], v[66:67] op_sel_hi:[1,1,0]
	v_pk_fma_f32 v[66:67], v[28:29], v[28:29], v[68:69] op_sel_hi:[1,1,0]
	v_pk_add_f32 v[60:61], v[60:61], v[60:61] op_sel:[0,1] op_sel_hi:[1,0]
	v_pk_add_f32 v[58:59], v[58:59], v[58:59] op_sel:[0,1] op_sel_hi:[1,0]
	v_mov_b32_e32 v63, v72
	v_mov_b32_e32 v67, v73
	v_mov_b32_e32 v61, v13
	v_mov_b32_e32 v59, v69
	v_pk_add_f32 v[62:63], v[62:63], v[66:67]
	v_pk_add_f32 v[58:59], v[60:61], v[58:59]
	s_waitcnt vmcnt(15)
	v_pk_add_f32 v[76:77], v[32:33], 1.0 op_sel_hi:[1,0]
	v_pk_add_f32 v[58:59], v[58:59], v[62:63]
	v_pk_add_f32 v[74:75], v[30:31], 1.0 op_sel_hi:[1,0]
	v_add_f32_e32 v13, v58, v59
	s_nop 1
	v_add_f32_dpp v13, v13, v13 quad_perm:[1,0,3,2] row_mask:0xf bank_mask:0xf
	s_waitcnt vmcnt(14)
	v_pk_add_f32 v[122:123], v[36:37], 1.0 op_sel_hi:[1,0]
	v_pk_add_f32 v[78:79], v[34:35], 1.0 op_sel_hi:[1,0]
	s_nop 1
	v_add_f32_dpp v13, v13, v13 quad_perm:[2,3,0,1] row_mask:0xf bank_mask:0xf
	s_nop 1
	v_add_f32_dpp v13, v13, v13 row_half_mirror row_mask:0xf bank_mask:0xf
	s_nop 1
	v_add_f32_dpp v13, v13, v13 row_mirror row_mask:0xf bank_mask:0xf
	s_nop 1
	v_mov_b32_e32 v60, v13
	s_nop 1
	v_permlane16_swap_b32_e32 v13, v60
	s_nop 0
	v_add_f32_e32 v13, v13, v60
	s_nop 1
	v_mov_b32_e32 v60, v13
	s_nop 1
	v_permlane32_swap_b32_e32 v13, v60
	s_nop 0
	v_add_f32_e32 v13, v13, v60
	v_lshl_add_u64 v[58:59], v[0:1], 0, s[16:17]
	v_fmamk_f32 v13, v13, 0x3a800000, v12
	v_mul_f32_e32 v60, 0x4b800000, v13
	v_cmp_gt_f32_e32 vcc, s1, v13
	s_nop 1
	v_cndmask_b32_e32 v13, v13, v60, vcc
	v_rsq_f32_e32 v13, v13
	s_nop 0
	v_mul_f32_e32 v60, 0x45800000, v13
	v_cndmask_b32_e32 v60, v13, v60, vcc
	v_pk_mul_f32 v[16:17], v[60:61], v[16:17] op_sel_hi:[0,1]
	v_pk_mul_f32 v[14:15], v[60:61], v[14:15] op_sel_hi:[0,1]
	v_pk_mul_f32 v[20:21], v[60:61], v[20:21] op_sel_hi:[0,1]
	v_pk_mul_f32 v[18:19], v[60:61], v[18:19] op_sel_hi:[0,1]
	s_waitcnt vmcnt(12)
	v_pk_mul_f32 v[14:15], v[42:43], v[14:15]
	v_pk_mul_f32 v[16:17], v[44:45], v[16:17]
	v_pk_mul_f32 v[18:19], v[38:39], v[18:19]
	v_pk_mul_f32 v[20:21], v[40:41], v[20:21]
	s_waitcnt vmcnt(10)
	v_pk_fma_f32 v[16:17], v[76:77], v[16:17], v[52:53]
	v_pk_fma_f32 v[14:15], v[74:75], v[14:15], v[50:51]
	v_pk_fma_f32 v[20:21], v[122:123], v[20:21], v[48:49]
	v_pk_fma_f32 v[18:19], v[78:79], v[18:19], v[46:47]
	v_cvt_pk_bf16_f32 v14, v14, v15
	v_cvt_pk_bf16_f32 v15, v16, v17
	v_cvt_pk_bf16_f32 v16, v18, v19
	v_cvt_pk_bf16_f32 v17, v20, v21
	global_store_dwordx2 v[58:59], v[14:15], off sc1
	global_store_dwordx2 v[58:59], v[16:17], off offset:512 sc1
	v_pk_mul_f32 v[28:29], v[60:61], v[28:29] op_sel_hi:[0,1]
	v_pk_mul_f32 v[26:27], v[60:61], v[26:27] op_sel_hi:[0,1]
	v_pk_mul_f32 v[24:25], v[60:61], v[24:25] op_sel_hi:[0,1]
	v_pk_mul_f32 v[22:23], v[60:61], v[22:23] op_sel_hi:[0,1]
	s_waitcnt vmcnt(11)
	v_pk_add_f32 v[16:17], v[82:83], 1.0 op_sel_hi:[1,0]
	v_pk_add_f32 v[14:15], v[80:81], 1.0 op_sel_hi:[1,0]
	s_waitcnt vmcnt(10)
	v_pk_mul_f32 v[18:19], v[84:85], v[26:27]
	v_pk_mul_f32 v[20:21], v[86:87], v[28:29]
	s_waitcnt vmcnt(9)
	v_pk_add_f32 v[26:27], v[90:91], 1.0 op_sel_hi:[1,0]
	v_pk_add_f32 v[28:29], v[88:89], 1.0 op_sel_hi:[1,0]
	s_waitcnt vmcnt(8)
	v_pk_mul_f32 v[22:23], v[92:93], v[22:23]
	v_pk_mul_f32 v[24:25], v[94:95], v[24:25]
	s_waitcnt vmcnt(7)
	v_pk_fma_f32 v[16:17], v[16:17], v[20:21], v[98:99]
	v_pk_fma_f32 v[14:15], v[14:15], v[18:19], v[96:97]
	s_waitcnt vmcnt(6)
	v_pk_fma_f32 v[18:19], v[26:27], v[24:25], v[102:103]
	v_pk_fma_f32 v[20:21], v[28:29], v[22:23], v[100:101]
	v_cvt_pk_bf16_f32 v14, v14, v15
	v_cvt_pk_bf16_f32 v15, v16, v17
	v_cvt_pk_bf16_f32 v16, v20, v21
	v_cvt_pk_bf16_f32 v17, v18, v19
	global_store_dwordx2 v[58:59], v[14:15], off offset:1024 sc1
	global_store_dwordx2 v[58:59], v[16:17], off offset:1536 sc1
	s_cmp_lg_u32 s40, 0
	s_cbranch_scc0 .Lp1_loopB
	s_branch .Lp1_exit

; __device__ __forceinline__ float wave_sum(float v) {
; #pragma unroll
;     for (int o = 1; o < 64; o <<= 1) v += __shfl_xor(v, o);
;     return v;
; }
.Lp1_joinB:
	s_waitcnt vmcnt(12)
	v_mov_b32_e32 v14, v130
	v_mov_b32_e32 v15, v131
	v_mov_b32_e32 v16, v132
	v_mov_b32_e32 v17, v133
	v_mov_b32_e32 v18, v134
	v_mov_b32_e32 v19, v135
	v_mov_b32_e32 v20, v136
	v_mov_b32_e32 v21, v137
	v_mov_b32_e32 v22, v138
	v_mov_b32_e32 v23, v139
	v_mov_b32_e32 v24, v140
	v_mov_b32_e32 v25, v141
	v_mov_b32_e32 v26, v142
	v_mov_b32_e32 v27, v143
	v_mov_b32_e32 v28, v144
	v_mov_b32_e32 v29, v145
	s_mov_b32 s37, s23
	s_add_i32 s23, s23, s32
	s_add_i32 s36, s23, s32
	s_cmp_ge_i32 s36, s0
	s_cselect_b32 s36, s37, s36
	s_cmp_ge_i32 s23, s0
	s_cselect_b32 s40, 1, 0
	s_mov_b32 s34, s36
	s_cmpk_gt_i32 s34, 0x7fff
	s_cselect_b32 s20, s6, s4
	s_cselect_b32 s21, s7, s5
	s_cselect_b32 s8, 0x8000, 0
	s_sub_i32 s8, s34, s8
	s_lshl_b64 s[38:39], s[8:9], 12
	s_add_u32 s20, s20, s38
	s_addc_u32 s21, s21, s39
	v_lshl_add_u64 v[120:121], s[20:21], 0, v[4:5]
	global_load_dwordx4 v[130:133], v[120:121], off nt
	global_load_dwordx4 v[134:137], v[120:121], off offset:1024 nt
	global_load_dwordx4 v[138:141], v[120:121], off offset:3072 nt
	global_load_dwordx4 v[142:145], v[120:121], off offset:2048 nt
	s_lshl_b64 s[16:17], s[16:17], 11
	v_pk_mul_f32 v[58:59], v[16:17], v[16:17]
	v_pk_mul_f32 v[60:61], v[14:15], v[14:15]
	v_pk_mul_f32 v[62:63], v[20:21], v[20:21]
	v_pk_mul_f32 v[64:65], v[18:19], v[18:19]
	v_pk_mov_b32 v[70:71], v[60:61], v[58:59] op_sel:[1,0]
	v_mov_b32_e32 v61, v59
	v_pk_mov_b32 v[58:59], v[64:65], v[62:63] op_sel:[1,0]
	v_mov_b32_e32 v65, v63
	v_mul_f32_e32 v69, v23, v23
	v_mul_f32_e32 v66, v27, v27
	v_mul_f32_e32 v68, v29, v29
	v_pk_add_f32 v[60:61], v[70:71], v[60:61]
	v_pk_add_f32 v[58:59], v[58:59], v[64:65]
	v_mul_f32_e32 v13, v22, v22
	v_mul_f32_e32 v72, v24, v24
	v_mul_f32_e32 v73, v25, v25
	v_pk_fma_f32 v[62:63], v[26:27], v[26:27], v[66:67] op_sel_hi:[1,1,0]
	v_pk_fma_f32 v[66:67], v[28:29], v[28:29], v[68:69] op_sel_hi:[1,1,0]
	v_pk_add_f32 v[60:61], v[60:61], v[60:61] op_sel:[0,1] op_sel_hi:[1,0]
	v_pk_add_f32 v[58:59], v[58:59], v[58:59] op_sel:[0,1] op_sel_hi:[1,0]
	v_mov_b32_e32 v63, v72
	v_mov_b32_e32 v67, v73
	v_mov_b32_e32 v61, v13
	v_mov_b32_e32 v59, v69
	v_pk_add_f32 v[62:63], v[62:63], v[66:67]
	v_pk_add_f32 v[58:59], v[60:61], v[58:59]
	s_waitcnt vmcnt(15)
	v_pk_add_f32 v[76:77], v[32:33], 1.0 op_sel_hi:[1,0]
	v_pk_add_f32 v[58:59], v[58:59], v[62:63]
	v_pk_add_f32 v[74:75], v[30:31], 1.0 op_sel_hi:[1,0]
	v_add_f32_e32 v13, v58, v59
	s_nop 1
	v_add_f32_dpp v13, v13, v13 quad_perm:[1,0,3,2] row_mask:0xf bank_mask:0xf
	s_waitcnt vmcnt(14)
	v_pk_add_f32 v[122:123], v[36:37], 1.0 op_sel_hi:[1,0]
	v_pk_add_f32 v[78:79], v[34:35], 1.0 op_sel_hi:[1,0]
	s_nop 1
	v_add_f32_dpp v13, v13, v13 quad_perm:[2,3,0,1] row_mask:0xf bank_mask:0xf
	s_nop 1
	v_add_f32_dpp v13, v13, v13 row_half_mirror row_mask:0xf bank_mask:0xf
	s_nop 1
	v_add_f32_dpp v13, v13, v13 row_mirror row_mask:0xf bank_mask:0xf
	s_nop 1
	v_mov_b32_e32 v60, v13
	s_nop 1
	v_permlane16_swap_b32_e32 v13, v60
	s_nop 0
	v_add_f32_e32 v13, v13, v60
	s_nop 1
	v_mov_b32_e32 v60, v13
	s_nop 1
	v_permlane32_swap_b32_e32 v13, v60
	s_nop 0
	v_add_f32_e32 v13, v13, v60
	v_lshl_add_u64 v[58:59], v[0:1], 0, s[16:17]
	v_fmamk_f32 v13, v13, 0x3a800000, v12
	v_mul_f32_e32 v60, 0x4b800000, v13
	v_cmp_gt_f32_e32 vcc, s1, v13
	s_nop 1
	v_cndmask_b32_e32 v13, v13, v60, vcc
	v_rsq_f32_e32 v13, v13
	s_nop 0
	v_mul_f32_e32 v60, 0x45800000, v13
	v_cndmask_b32_e32 v60, v13, v60, vcc
	v_pk_mul_f32 v[16:17], v[60:61], v[16:17] op_sel_hi:[0,1]
	v_pk_mul_f32 v[14:15], v[60:61], v[14:15] op_sel_hi:[0,1]
	v_pk_mul_f32 v[20:21], v[60:61], v[20:21] op_sel_hi:[0,1]
	v_pk_mul_f32 v[18:19], v[60:61], v[18:19] op_sel_hi:[0,1]
	s_waitcnt vmcnt(12)
	v_pk_mul_f32 v[14:15], v[42:43], v[14:15]
	v_pk_mul_f32 v[16:17], v[44:45], v[16:17]
	v_pk_mul_f32 v[18:19], v[38:39], v[18:19]
	v_pk_mul_f32 v[20:21], v[40:41], v[20:21]
	s_waitcnt vmcnt(10)
	v_pk_fma_f32 v[16:17], v[76:77], v[16:17], v[52:53]
	v_pk_fma_f32 v[14:15], v[74:75], v[14:15], v[50:51]
	v_pk_fma_f32 v[20:21], v[122:123], v[20:21], v[48:49]
	v_pk_fma_f32 v[18:19], v[78:79], v[18:19], v[46:47]
	v_cvt_pk_bf16_f32 v14, v14, v15
	v_cvt_pk_bf16_f32 v15, v16, v17
	v_cvt_pk_bf16_f32 v16, v18, v19
	v_cvt_pk_bf16_f32 v17, v20, v21
	global_store_dwordx2 v[58:59], v[14:15], off sc1
	global_store_dwordx2 v[58:59], v[16:17], off offset:512 sc1
	v_pk_mul_f32 v[28:29], v[60:61], v[28:29] op_sel_hi:[0,1]
	v_pk_mul_f32 v[26:27], v[60:61], v[26:27] op_sel_hi:[0,1]
	v_pk_mul_f32 v[24:25], v[60:61], v[24:25] op_sel_hi:[0,1]
	v_pk_mul_f32 v[22:23], v[60:61], v[22:23] op_sel_hi:[0,1]
	s_waitcnt vmcnt(11)
	v_pk_add_f32 v[16:17], v[82:83], 1.0 op_sel_hi:[1,0]
	v_pk_add_f32 v[14:15], v[80:81], 1.0 op_sel_hi:[1,0]
	s_waitcnt vmcnt(10)
	v_pk_mul_f32 v[18:19], v[84:85], v[26:27]
	v_pk_mul_f32 v[20:21], v[86:87], v[28:29]
	s_waitcnt vmcnt(9)
	v_pk_add_f32 v[26:27], v[90:91], 1.0 op_sel_hi:[1,0]
	v_pk_add_f32 v[28:29], v[88:89], 1.0 op_sel_hi:[1,0]
	s_waitcnt vmcnt(8)
	v_pk_mul_f32 v[22:23], v[92:93], v[22:23]
	v_pk_mul_f32 v[24:25], v[94:95], v[24:25]
	s_waitcnt vmcnt(7)
	v_pk_fma_f32 v[16:17], v[16:17], v[20:21], v[98:99]
	v_pk_fma_f32 v[14:15], v[14:15], v[18:19], v[96:97]
	s_waitcnt vmcnt(6)
	v_pk_fma_f32 v[18:19], v[26:27], v[24:25], v[102:103]
	v_pk_fma_f32 v[20:21], v[28:29], v[22:23], v[100:101]
	v_cvt_pk_bf16_f32 v14, v14, v15
	v_cvt_pk_bf16_f32 v15, v16, v17
	v_cvt_pk_bf16_f32 v16, v20, v21
	v_cvt_pk_bf16_f32 v17, v18, v19
	global_store_dwordx2 v[58:59], v[14:15], off offset:1024 sc1
	global_store_dwordx2 v[58:59], v[16:17], off offset:1536 sc1
	s_cmp_lg_u32 s40, 0
	s_cbranch_scc0 .Lp1_loop
